# scan consumer: fourth LDS operand buffer in registers the consumer waves do not use otherwise, loads three steps ahead, one counted wait per two steps
# speedup vs baseline: 1.0532x; 1.0012x over previous
; __device__ __forceinline__ void rwkv_prompt_unit(const Params& p, int l, int b, int h, int ibase, float* sf) {
;     ...
;             const float* bf_ = sf + (c & 1) * 12288 + jg; float* sY = sYb + (c & 1) * 512; const float* vb_ = sf + (c & 1) * 12288 + 6144 + ibase + rl;
;             f32x4 R[2], W[2], K[2], A[2], B[2]; float V[2];
;     ...
;             RW_LOAD(R, W, K, A, B, V, 0);
;             float pyprev = 0.f;
; #pragma unroll
;             for (int g = 0; g < 16; ++g) {
;                 f32x4 Rn[2], Wn[2], Kn[2], An[2], Bn[2]; float Vn[2];
;                 if (g + 1 < 16) RW_LOAD(Rn, Wn, Kn, An, Bn, Vn, g + 1);
;                 __builtin_amdgcn_sched_barrier(0);
; #pragma unroll
;                 for (int u = 0; u < 2; ++u) {
;                     const f32x2v a01 = {A[u].x, A[u].y}, a23 = {A[u].z, A[u].w}, w01 = {W[u].x, W[u].y}, w23 = {W[u].z, W[u].w}, b01 = {B[u].x, B[u].y}, b23 = {B[u].z, B[u].w};
;                     const f32x2v k01 = {K[u].x, K[u].y}, k23 = {K[u].z, K[u].w}, r01 = {R[u].x, R[u].y}, r23 = {R[u].z, R[u].w};
;                     f32x2v pa = S01 * a01; pa = __builtin_elementwise_fma(S23, a23, pa);
;                     float ra = pa.x + pa.y, rb = pyprev;
;                     ra += dppf<0xB1, 0xF>(ra); rb += dppf<0xB1, 0xF>(rb);
;                     ra += dppf<0x4E, 0xF>(ra); rb += dppf<0x4E, 0xF>(rb);
;                     ra += dppf<0x124, 0xF>(ra); rb += dppf<0x124, 0xF>(rb);
;                     ra += dppf<0x128, 0xF>(ra); rb += dppf<0x128, 0xF>(rb);
;                     if ((g * 2 + u) > 0 && (lane & 15) == 0) sY[(g * 2 + u - 1) * 16 + rl] = rb;
;                     const f32x2v sa2 = {ra, ra}, v2 = {V[u], V[u]};
;                     S01 = __builtin_elementwise_fma(S01, w01, __builtin_elementwise_fma(sa2, b01, v2 * k01));
;                     S23 = __builtin_elementwise_fma(S23, w23, __builtin_elementwise_fma(sa2, b23, v2 * k23));
;                     f32x2v py = S01 * r01; py = __builtin_elementwise_fma(S23, r23, py);
;                     pyprev = py.x + py.y;
;                 }
;                 __builtin_amdgcn_sched_barrier(0);
;                 if (g + 1 < 16) {
; #pragma unroll
;                     for (int u = 0; u < 2; ++u) { R[u] = Rn[u]; W[u] = Wn[u]; K[u] = Kn[u]; A[u] = An[u]; B[u] = Bn[u]; V[u] = Vn[u]; }
.LBB0_964:
	s_and_b64 vcc, exec, s[8:9]
	s_cbranch_vccz .LBB0_1029
	s_setprio 0
	s_and_b32 s8, s15, 1
	s_mul_i32 s9, s8, 0xc000
	v_lshl_add_u32 v212, v176, 2, s9
	s_add_i32 s9, s9, s11
	v_lshl_add_u32 v213, v210, 2, s9
	ds_read_b128 v[50:53], v212 offset:32768
	ds_read_b128 v[62:65], v212 offset:16384
	ds_read_b128 v[54:57], v212 offset:8192
	ds_read_b128 v[58:61], v212 offset:40960
	ds_read_b128 v[66:69], v212 offset:0
	ds_read2st64_b32 v[110:111], v213 offset0:96 offset1:97
	ds_read_b128 v[70:73], v212 offset:33024
	ds_read_b128 v[82:85], v212 offset:16640
	ds_read_b128 v[74:77], v212 offset:8448
	ds_read_b128 v[78:81], v212 offset:41216
	ds_read_b128 v[86:89], v212 offset:256
	ds_read_b128 v[90:93], v212 offset:33280
	ds_read_b128 v[102:105], v212 offset:16896
	ds_read_b128 v[94:97], v212 offset:8704
	ds_read_b128 v[98:101], v212 offset:41472
	ds_read_b128 v[106:109], v212 offset:512
	ds_read2st64_b32 v[112:113], v213 offset0:98 offset1:99
	s_lshl_b32 s8, s8, 11
	s_add_i32 s8, s8, 0x18000
	v_lshl_add_u32 v211, v210, 2, s8
	v_and_b32_e32 v137, 3, v207
	v_lshl_add_u32 v211, v137, 6, v211
	s_add_i32 s8, s8, 0x1000
	v_and_b32_e32 v137, 63, v207
	v_lshl_add_u32 v137, v137, 2, s8
	v_and_b32_e32 v186, 15, v207
	v_cmp_gt_u32_e32 vcc, 4, v186
	s_nop 1
	v_cndmask_b32_e32 v211, v137, v211, vcc
	v_and_b32_e32 v186, 1, v207
	v_cmp_ne_u32_e64 s[8:9], 0, v186
	v_and_b32_e32 v186, 2, v207
	v_cmp_ne_u32_e32 vcc, 0, v186
	s_waitcnt lgkmcnt(6)
	v_pk_mul_f32 v[114:115], v[46:47], v[50:51]
	s_nop 0
	v_pk_fma_f32 v[114:115], v[48:49], v[52:53], v[114:115]
	s_nop 0
	v_add_f32_e32 v116, v114, v115
	v_pk_mul_f32 v[120:121], v[62:63], v[110:111] op_sel_hi:[1,0]
	s_nop 0
	v_add_f32_dpp v116, v116, v116 quad_perm:[1,0,3,2] row_mask:0xf bank_mask:0xf bound_ctrl:1
	v_pk_mul_f32 v[122:123], v[64:65], v[110:111] op_sel_hi:[1,0]
	v_pk_fma_f32 v[124:125], v[46:47], v[54:55], v[120:121]
	v_add_f32_dpp v116, v116, v116 quad_perm:[2,3,0,1] row_mask:0xf bank_mask:0xf bound_ctrl:1
	v_pk_fma_f32 v[126:127], v[48:49], v[56:57], v[122:123]
	s_nop 0
	v_add_f32_dpp v116, v116, v116 row_ror:4 row_mask:0xf bank_mask:0xf bound_ctrl:1
	s_nop 1
	v_add_f32_dpp v116, v116, v116 row_ror:8 row_mask:0xf bank_mask:0xf bound_ctrl:1
	v_pk_fma_f32 v[46:47], v[116:117], v[58:59], v[124:125] op_sel_hi:[0,1,1]
	v_pk_fma_f32 v[48:49], v[116:117], v[60:61], v[126:127] op_sel_hi:[0,1,1]
	ds_read_b128 v[30:33], v212 offset:33536
	ds_read_b128 v[42:45], v212 offset:17152
	ds_read_b128 v[34:37], v212 offset:8960
	ds_read_b128 v[38:41], v212 offset:41728
	ds_read_b128 v[140:143], v212 offset:768
	v_pk_mul_f32 v[114:115], v[46:47], v[70:71]
	v_pk_mul_f32 v[118:119], v[46:47], v[66:67]
	v_pk_fma_f32 v[114:115], v[48:49], v[72:73], v[114:115]
	v_pk_fma_f32 v[118:119], v[48:49], v[68:69], v[118:119]
	v_add_f32_e32 v116, v114, v115
	v_add_f32_e32 v129, v118, v119
	v_pk_mul_f32 v[120:121], v[82:83], v[110:111] op_sel:[0,1] op_sel_hi:[1,1]
	v_add_f32_dpp v116, v116, v116 quad_perm:[1,0,3,2] row_mask:0xf bank_mask:0xf bound_ctrl:1
	v_pk_mul_f32 v[122:123], v[84:85], v[110:111] op_sel:[0,1] op_sel_hi:[1,1]
	v_pk_fma_f32 v[124:125], v[46:47], v[74:75], v[120:121]
	v_add_f32_dpp v116, v116, v116 quad_perm:[2,3,0,1] row_mask:0xf bank_mask:0xf bound_ctrl:1
	v_pk_fma_f32 v[126:127], v[48:49], v[76:77], v[122:123]
	s_nop 0
	v_add_f32_dpp v116, v116, v116 row_ror:4 row_mask:0xf bank_mask:0xf bound_ctrl:1
	s_nop 1
	v_add_f32_dpp v116, v116, v116 row_ror:8 row_mask:0xf bank_mask:0xf bound_ctrl:1
	v_pk_fma_f32 v[46:47], v[116:117], v[78:79], v[124:125] op_sel_hi:[0,1,1]
	v_pk_fma_f32 v[48:49], v[116:117], v[80:81], v[126:127] op_sel_hi:[0,1,1]
	ds_read_b128 v[50:53], v212 offset:33792
	ds_read_b128 v[62:65], v212 offset:17408
	ds_read_b128 v[54:57], v212 offset:9216
	ds_read_b128 v[58:61], v212 offset:41984
	ds_read_b128 v[66:69], v212 offset:1024
	ds_read2st64_b32 v[110:111], v213 offset0:100 offset1:101
	s_waitcnt lgkmcnt(6)
	v_pk_mul_f32 v[114:115], v[46:47], v[90:91]
	v_pk_mul_f32 v[118:119], v[46:47], v[86:87]
	v_pk_fma_f32 v[114:115], v[48:49], v[92:93], v[114:115]
	v_pk_fma_f32 v[118:119], v[48:49], v[88:89], v[118:119]
	v_add_f32_e32 v116, v114, v115
	v_add_f32_e32 v130, v118, v119
	v_pk_mul_f32 v[120:121], v[102:103], v[112:113] op_sel_hi:[1,0]
	v_add_f32_dpp v116, v116, v116 quad_perm:[1,0,3,2] row_mask:0xf bank_mask:0xf bound_ctrl:1
	v_pk_mul_f32 v[122:123], v[104:105], v[112:113] op_sel_hi:[1,0]
	v_pk_fma_f32 v[124:125], v[46:47], v[94:95], v[120:121]
	v_add_f32_dpp v116, v116, v116 quad_perm:[2,3,0,1] row_mask:0xf bank_mask:0xf bound_ctrl:1
	v_pk_fma_f32 v[126:127], v[48:49], v[96:97], v[122:123]
	s_nop 0
	v_add_f32_dpp v116, v116, v116 row_ror:4 row_mask:0xf bank_mask:0xf bound_ctrl:1
	s_nop 1
	v_add_f32_dpp v116, v116, v116 row_ror:8 row_mask:0xf bank_mask:0xf bound_ctrl:1
	v_pk_fma_f32 v[46:47], v[116:117], v[98:99], v[124:125] op_sel_hi:[0,1,1]
	v_pk_fma_f32 v[48:49], v[116:117], v[100:101], v[126:127] op_sel_hi:[0,1,1]
	ds_read_b128 v[70:73], v212 offset:34048
	ds_read_b128 v[82:85], v212 offset:17664
	ds_read_b128 v[74:77], v212 offset:9472
	ds_read_b128 v[78:81], v212 offset:42240
	ds_read_b128 v[86:89], v212 offset:1280
	v_pk_mul_f32 v[114:115], v[46:47], v[30:31]
	v_pk_mul_f32 v[118:119], v[46:47], v[106:107]
	v_pk_fma_f32 v[114:115], v[48:49], v[32:33], v[114:115]
	v_pk_fma_f32 v[118:119], v[48:49], v[108:109], v[118:119]
	v_add_f32_e32 v116, v114, v115
	v_add_f32_e32 v131, v118, v119
	v_pk_mul_f32 v[120:121], v[42:43], v[112:113] op_sel:[0,1] op_sel_hi:[1,1]
	v_add_f32_dpp v116, v116, v116 quad_perm:[1,0,3,2] row_mask:0xf bank_mask:0xf bound_ctrl:1
	v_pk_mul_f32 v[122:123], v[44:45], v[112:113] op_sel:[0,1] op_sel_hi:[1,1]
	v_pk_fma_f32 v[124:125], v[46:47], v[34:35], v[120:121]
	v_add_f32_dpp v116, v116, v116 quad_perm:[2,3,0,1] row_mask:0xf bank_mask:0xf bound_ctrl:1
	v_pk_fma_f32 v[126:127], v[48:49], v[36:37], v[122:123]
	s_nop 0
	v_add_f32_dpp v116, v116, v116 row_ror:4 row_mask:0xf bank_mask:0xf bound_ctrl:1
	s_nop 1
	v_add_f32_dpp v116, v116, v116 row_ror:8 row_mask:0xf bank_mask:0xf bound_ctrl:1
	v_pk_fma_f32 v[46:47], v[116:117], v[38:39], v[124:125] op_sel_hi:[0,1,1]
	v_pk_fma_f32 v[48:49], v[116:117], v[40:41], v[126:127] op_sel_hi:[0,1,1]
	ds_read_b128 v[90:93], v212 offset:34304
	ds_read_b128 v[102:105], v212 offset:17920
	ds_read_b128 v[94:97], v212 offset:9728
	ds_read_b128 v[98:101], v212 offset:42496
	ds_read_b128 v[106:109], v212 offset:1536
	ds_read2st64_b32 v[112:113], v213 offset0:102 offset1:103
	s_waitcnt lgkmcnt(6)
; __device__ __forceinline__ void rwkv_prompt_unit(const Params& p, int l, int b, int h, int ibase, float* sf) {
;     ...
;             for (int g = 0; g < 16; ++g) {
;                 f32x4 Rn[2], Wn[2], Kn[2], An[2], Bn[2]; float Vn[2];
;                 if (g + 1 < 16) RW_LOAD(Rn, Wn, Kn, An, Bn, Vn, g + 1);
;                 __builtin_amdgcn_sched_barrier(0);
; #pragma unroll
;                 for (int u = 0; u < 2; ++u) {
;                     const f32x2v a01 = {A[u].x, A[u].y}, a23 = {A[u].z, A[u].w}, w01 = {W[u].x, W[u].y}, w23 = {W[u].z, W[u].w}, b01 = {B[u].x, B[u].y}, b23 = {B[u].z, B[u].w};
;                     const f32x2v k01 = {K[u].x, K[u].y}, k23 = {K[u].z, K[u].w}, r01 = {R[u].x, R[u].y}, r23 = {R[u].z, R[u].w};
;                     f32x2v pa = S01 * a01; pa = __builtin_elementwise_fma(S23, a23, pa);
;                     float ra = pa.x + pa.y, rb = pyprev;
;                     ra += dppf<0xB1, 0xF>(ra); rb += dppf<0xB1, 0xF>(rb);
;                     ra += dppf<0x4E, 0xF>(ra); rb += dppf<0x4E, 0xF>(rb);
;                     ra += dppf<0x124, 0xF>(ra); rb += dppf<0x124, 0xF>(rb);
;                     ra += dppf<0x128, 0xF>(ra); rb += dppf<0x128, 0xF>(rb);
;                     if ((g * 2 + u) > 0 && (lane & 15) == 0) sY[(g * 2 + u - 1) * 16 + rl] = rb;
;                     const f32x2v sa2 = {ra, ra}, v2 = {V[u], V[u]};
;                     S01 = __builtin_elementwise_fma(S01, w01, __builtin_elementwise_fma(sa2, b01, v2 * k01));
;                     S23 = __builtin_elementwise_fma(S23, w23, __builtin_elementwise_fma(sa2, b23, v2 * k23));
;                     f32x2v py = S01 * r01; py = __builtin_elementwise_fma(S23, r23, py);
;                     pyprev = py.x + py.y;
;                 }
;                 __builtin_amdgcn_sched_barrier(0);
;                 if (g + 1 < 16) {
; #pragma unroll
;                     for (int u = 0; u < 2; ++u) { R[u] = Rn[u]; W[u] = Wn[u]; K[u] = Kn[u]; A[u] = An[u]; B[u] = Bn[u]; V[u] = Vn[u]; }
	v_pk_mul_f32 v[114:115], v[46:47], v[50:51]
	v_pk_mul_f32 v[118:119], v[46:47], v[140:141]
	v_pk_fma_f32 v[114:115], v[48:49], v[52:53], v[114:115]
	v_pk_fma_f32 v[118:119], v[48:49], v[142:143], v[118:119]
	v_add_f32_e32 v116, v114, v115
	v_add_f32_e32 v132, v118, v119
	v_pk_mul_f32 v[120:121], v[62:63], v[110:111] op_sel_hi:[1,0]
	v_add_f32_dpp v116, v116, v116 quad_perm:[1,0,3,2] row_mask:0xf bank_mask:0xf bound_ctrl:1
	v_pk_mul_f32 v[122:123], v[64:65], v[110:111] op_sel_hi:[1,0]
	v_pk_fma_f32 v[124:125], v[46:47], v[54:55], v[120:121]
	v_add_f32_dpp v116, v116, v116 quad_perm:[2,3,0,1] row_mask:0xf bank_mask:0xf bound_ctrl:1
	v_pk_fma_f32 v[126:127], v[48:49], v[56:57], v[122:123]
	v_cndmask_b32_e64 v137, v129, v130, s[8:9]
	v_add_f32_dpp v116, v116, v116 row_ror:4 row_mask:0xf bank_mask:0xf bound_ctrl:1
	v_cndmask_b32_e64 v186, v130, v129, s[8:9]
	s_nop 1
	v_add_f32_dpp v187, v186, v137 quad_perm:[1,0,3,2] row_mask:0xf bank_mask:0xf bound_ctrl:1
	v_add_f32_dpp v116, v116, v116 row_ror:8 row_mask:0xf bank_mask:0xf bound_ctrl:1
	v_pk_fma_f32 v[46:47], v[116:117], v[58:59], v[124:125] op_sel_hi:[0,1,1]
	v_pk_fma_f32 v[48:49], v[116:117], v[60:61], v[126:127] op_sel_hi:[0,1,1]
	ds_read_b128 v[30:33], v212 offset:34560
	ds_read_b128 v[42:45], v212 offset:18176
	ds_read_b128 v[34:37], v212 offset:9984
	ds_read_b128 v[38:41], v212 offset:42752
	ds_read_b128 v[140:143], v212 offset:1792
	v_pk_mul_f32 v[114:115], v[46:47], v[70:71]
	v_pk_mul_f32 v[118:119], v[46:47], v[66:67]
	v_pk_fma_f32 v[114:115], v[48:49], v[72:73], v[114:115]
	v_pk_fma_f32 v[118:119], v[48:49], v[68:69], v[118:119]
	v_add_f32_e32 v116, v114, v115
	v_add_f32_e32 v133, v118, v119
	v_pk_mul_f32 v[120:121], v[82:83], v[110:111] op_sel:[0,1] op_sel_hi:[1,1]
	v_add_f32_dpp v116, v116, v116 quad_perm:[1,0,3,2] row_mask:0xf bank_mask:0xf bound_ctrl:1
	v_pk_mul_f32 v[122:123], v[84:85], v[110:111] op_sel:[0,1] op_sel_hi:[1,1]
	v_pk_fma_f32 v[124:125], v[46:47], v[74:75], v[120:121]
	v_add_f32_dpp v116, v116, v116 quad_perm:[2,3,0,1] row_mask:0xf bank_mask:0xf bound_ctrl:1
	v_pk_fma_f32 v[126:127], v[48:49], v[76:77], v[122:123]
	v_cndmask_b32_e64 v137, v131, v132, s[8:9]
	v_add_f32_dpp v116, v116, v116 row_ror:4 row_mask:0xf bank_mask:0xf bound_ctrl:1
	v_cndmask_b32_e64 v186, v132, v131, s[8:9]
	s_nop 1
	v_add_f32_dpp v188, v186, v137 quad_perm:[1,0,3,2] row_mask:0xf bank_mask:0xf bound_ctrl:1
	v_add_f32_dpp v116, v116, v116 row_ror:8 row_mask:0xf bank_mask:0xf bound_ctrl:1
	v_pk_fma_f32 v[46:47], v[116:117], v[78:79], v[124:125] op_sel_hi:[0,1,1]
	v_pk_fma_f32 v[48:49], v[116:117], v[80:81], v[126:127] op_sel_hi:[0,1,1]
	ds_read_b128 v[50:53], v212 offset:34816
	ds_read_b128 v[62:65], v212 offset:18432
	ds_read_b128 v[54:57], v212 offset:10240
	ds_read_b128 v[58:61], v212 offset:43008
	ds_read_b128 v[66:69], v212 offset:2048
	ds_read2st64_b32 v[110:111], v213 offset0:104 offset1:105
	s_waitcnt lgkmcnt(6)
	v_pk_mul_f32 v[114:115], v[46:47], v[90:91]
	v_pk_mul_f32 v[118:119], v[46:47], v[86:87]
	v_pk_fma_f32 v[114:115], v[48:49], v[92:93], v[114:115]
	v_pk_fma_f32 v[118:119], v[48:49], v[88:89], v[118:119]
	v_add_f32_e32 v116, v114, v115
	v_add_f32_e32 v134, v118, v119
	v_pk_mul_f32 v[120:121], v[102:103], v[112:113] op_sel_hi:[1,0]
	v_add_f32_dpp v116, v116, v116 quad_perm:[1,0,3,2] row_mask:0xf bank_mask:0xf bound_ctrl:1
	v_pk_mul_f32 v[122:123], v[104:105], v[112:113] op_sel_hi:[1,0]
	v_pk_fma_f32 v[124:125], v[46:47], v[94:95], v[120:121]
	v_add_f32_dpp v116, v116, v116 quad_perm:[2,3,0,1] row_mask:0xf bank_mask:0xf bound_ctrl:1
	v_pk_fma_f32 v[126:127], v[48:49], v[96:97], v[122:123]
	v_cndmask_b32_e32 v137, v187, v188, vcc
	v_add_f32_dpp v116, v116, v116 row_ror:4 row_mask:0xf bank_mask:0xf bound_ctrl:1
	v_cndmask_b32_e32 v186, v188, v187, vcc
	s_nop 1
	v_add_f32_dpp v189, v186, v137 quad_perm:[2,3,0,1] row_mask:0xf bank_mask:0xf bound_ctrl:1
	v_add_f32_dpp v116, v116, v116 row_ror:8 row_mask:0xf bank_mask:0xf bound_ctrl:1
	v_pk_fma_f32 v[46:47], v[116:117], v[98:99], v[124:125] op_sel_hi:[0,1,1]
	v_pk_fma_f32 v[48:49], v[116:117], v[100:101], v[126:127] op_sel_hi:[0,1,1]
	ds_read_b128 v[70:73], v212 offset:35072
	ds_read_b128 v[82:85], v212 offset:18688
	ds_read_b128 v[74:77], v212 offset:10496
	ds_read_b128 v[78:81], v212 offset:43264
	ds_read_b128 v[86:89], v212 offset:2304
	v_pk_mul_f32 v[114:115], v[46:47], v[30:31]
	v_pk_mul_f32 v[118:119], v[46:47], v[106:107]
	v_pk_fma_f32 v[114:115], v[48:49], v[32:33], v[114:115]
	v_pk_fma_f32 v[118:119], v[48:49], v[108:109], v[118:119]
	v_add_f32_e32 v116, v114, v115
	v_add_f32_e32 v135, v118, v119
	v_pk_mul_f32 v[120:121], v[42:43], v[112:113] op_sel:[0,1] op_sel_hi:[1,1]
	v_add_f32_dpp v116, v116, v116 quad_perm:[1,0,3,2] row_mask:0xf bank_mask:0xf bound_ctrl:1
	v_pk_mul_f32 v[122:123], v[44:45], v[112:113] op_sel:[0,1] op_sel_hi:[1,1]
	v_pk_fma_f32 v[124:125], v[46:47], v[34:35], v[120:121]
	v_add_f32_dpp v116, v116, v116 quad_perm:[2,3,0,1] row_mask:0xf bank_mask:0xf bound_ctrl:1
	v_pk_fma_f32 v[126:127], v[48:49], v[36:37], v[122:123]
	v_add_f32_dpp v189, v189, v189 row_ror:4 row_mask:0xf bank_mask:0xf bound_ctrl:1
	v_add_f32_dpp v116, v116, v116 row_ror:4 row_mask:0xf bank_mask:0xf bound_ctrl:1
	s_nop 0
	v_add_f32_dpp v189, v189, v189 row_ror:8 row_mask:0xf bank_mask:0xf bound_ctrl:1
	ds_write_b32 v211, v189 offset:0
	v_add_f32_dpp v116, v116, v116 row_ror:8 row_mask:0xf bank_mask:0xf bound_ctrl:1
	v_pk_fma_f32 v[46:47], v[116:117], v[38:39], v[124:125] op_sel_hi:[0,1,1]
	v_pk_fma_f32 v[48:49], v[116:117], v[40:41], v[126:127] op_sel_hi:[0,1,1]
	ds_read_b128 v[90:93], v212 offset:35328
	ds_read_b128 v[102:105], v212 offset:18944
	ds_read_b128 v[94:97], v212 offset:10752
	ds_read_b128 v[98:101], v212 offset:43520
	ds_read_b128 v[106:109], v212 offset:2560
	ds_read2st64_b32 v[112:113], v213 offset0:106 offset1:107
	s_waitcnt lgkmcnt(7)
; __device__ __forceinline__ void rwkv_prompt_unit(const Params& p, int l, int b, int h, int ibase, float* sf) {
;     ...
;             const float* bf_ = sf + (c & 1) * 12288 + jg; float* sY = sYb + (c & 1) * 512; const float* vb_ = sf + (c & 1) * 12288 + 6144 + ibase + rl;
;             f32x4 R[2], W[2], K[2], A[2], B[2]; float V[2];
;     ...
;             RW_LOAD(R, W, K, A, B, V, 0);
;             float pyprev = 0.f;
; #pragma unroll
;             for (int g = 0; g < 16; ++g) {
;                 f32x4 Rn[2], Wn[2], Kn[2], An[2], Bn[2]; float Vn[2];
;                 if (g + 1 < 16) RW_LOAD(Rn, Wn, Kn, An, Bn, Vn, g + 1);
;                 __builtin_amdgcn_sched_barrier(0);
; #pragma unroll
;                 for (int u = 0; u < 2; ++u) {
;                     const f32x2v a01 = {A[u].x, A[u].y}, a23 = {A[u].z, A[u].w}, w01 = {W[u].x, W[u].y}, w23 = {W[u].z, W[u].w}, b01 = {B[u].x, B[u].y}, b23 = {B[u].z, B[u].w};
;                     const f32x2v k01 = {K[u].x, K[u].y}, k23 = {K[u].z, K[u].w}, r01 = {R[u].x, R[u].y}, r23 = {R[u].z, R[u].w};
;                     f32x2v pa = S01 * a01; pa = __builtin_elementwise_fma(S23, a23, pa);
;                     float ra = pa.x + pa.y, rb = pyprev;
;                     ra += dppf<0xB1, 0xF>(ra); rb += dppf<0xB1, 0xF>(rb);
;                     ra += dppf<0x4E, 0xF>(ra); rb += dppf<0x4E, 0xF>(rb);
;                     ra += dppf<0x124, 0xF>(ra); rb += dppf<0x124, 0xF>(rb);
;                     ra += dppf<0x128, 0xF>(ra); rb += dppf<0x128, 0xF>(rb);
;                     if ((g * 2 + u) > 0 && (lane & 15) == 0) sY[(g * 2 + u - 1) * 16 + rl] = rb;
;                     const f32x2v sa2 = {ra, ra}, v2 = {V[u], V[u]};
;                     S01 = __builtin_elementwise_fma(S01, w01, __builtin_elementwise_fma(sa2, b01, v2 * k01));
;                     S23 = __builtin_elementwise_fma(S23, w23, __builtin_elementwise_fma(sa2, b23, v2 * k23));
;                     f32x2v py = S01 * r01; py = __builtin_elementwise_fma(S23, r23, py);
;                     pyprev = py.x + py.y;
;                 }
;                 __builtin_amdgcn_sched_barrier(0);
;                 if (g + 1 < 16) {
; #pragma unroll
;                     for (int u = 0; u < 2; ++u) { R[u] = Rn[u]; W[u] = Wn[u]; K[u] = Kn[u]; A[u] = An[u]; B[u] = Bn[u]; V[u] = Vn[u]; }
;                 }
;             }
	v_pk_mul_f32 v[114:115], v[46:47], v[50:51]
	v_pk_mul_f32 v[118:119], v[46:47], v[140:141]
	v_pk_fma_f32 v[114:115], v[48:49], v[52:53], v[114:115]
	v_pk_fma_f32 v[118:119], v[48:49], v[142:143], v[118:119]
	v_add_f32_e32 v116, v114, v115
	v_add_f32_e32 v136, v118, v119
	v_pk_mul_f32 v[120:121], v[62:63], v[110:111] op_sel_hi:[1,0]
	v_add_f32_dpp v116, v116, v116 quad_perm:[1,0,3,2] row_mask:0xf bank_mask:0xf bound_ctrl:1
	v_pk_mul_f32 v[122:123], v[64:65], v[110:111] op_sel_hi:[1,0]
	v_pk_fma_f32 v[124:125], v[46:47], v[54:55], v[120:121]
	v_add_f32_dpp v116, v116, v116 quad_perm:[2,3,0,1] row_mask:0xf bank_mask:0xf bound_ctrl:1
	v_pk_fma_f32 v[126:127], v[48:49], v[56:57], v[122:123]
	v_cndmask_b32_e64 v137, v133, v134, s[8:9]
	v_add_f32_dpp v116, v116, v116 row_ror:4 row_mask:0xf bank_mask:0xf bound_ctrl:1
	v_cndmask_b32_e64 v186, v134, v133, s[8:9]
	s_nop 1
	v_add_f32_dpp v187, v186, v137 quad_perm:[1,0,3,2] row_mask:0xf bank_mask:0xf bound_ctrl:1
	v_add_f32_dpp v116, v116, v116 row_ror:8 row_mask:0xf bank_mask:0xf bound_ctrl:1
	v_pk_fma_f32 v[46:47], v[116:117], v[58:59], v[124:125] op_sel_hi:[0,1,1]
	v_pk_fma_f32 v[48:49], v[116:117], v[60:61], v[126:127] op_sel_hi:[0,1,1]
	ds_read_b128 v[30:33], v212 offset:35584
	ds_read_b128 v[42:45], v212 offset:19200
	ds_read_b128 v[34:37], v212 offset:11008
	ds_read_b128 v[38:41], v212 offset:43776
	ds_read_b128 v[140:143], v212 offset:2816
	v_pk_mul_f32 v[114:115], v[46:47], v[70:71]
	v_pk_mul_f32 v[118:119], v[46:47], v[66:67]
	v_pk_fma_f32 v[114:115], v[48:49], v[72:73], v[114:115]
	v_pk_fma_f32 v[118:119], v[48:49], v[68:69], v[118:119]
	v_add_f32_e32 v116, v114, v115
	v_add_f32_e32 v129, v118, v119
	v_pk_mul_f32 v[120:121], v[82:83], v[110:111] op_sel:[0,1] op_sel_hi:[1,1]
	v_add_f32_dpp v116, v116, v116 quad_perm:[1,0,3,2] row_mask:0xf bank_mask:0xf bound_ctrl:1
	v_pk_mul_f32 v[122:123], v[84:85], v[110:111] op_sel:[0,1] op_sel_hi:[1,1]
	v_pk_fma_f32 v[124:125], v[46:47], v[74:75], v[120:121]
	v_add_f32_dpp v116, v116, v116 quad_perm:[2,3,0,1] row_mask:0xf bank_mask:0xf bound_ctrl:1
	v_pk_fma_f32 v[126:127], v[48:49], v[76:77], v[122:123]
	v_cndmask_b32_e64 v137, v135, v136, s[8:9]
	v_add_f32_dpp v116, v116, v116 row_ror:4 row_mask:0xf bank_mask:0xf bound_ctrl:1
	v_cndmask_b32_e64 v186, v136, v135, s[8:9]
	s_nop 1
	v_add_f32_dpp v188, v186, v137 quad_perm:[1,0,3,2] row_mask:0xf bank_mask:0xf bound_ctrl:1
	v_add_f32_dpp v116, v116, v116 row_ror:8 row_mask:0xf bank_mask:0xf bound_ctrl:1
	v_pk_fma_f32 v[46:47], v[116:117], v[78:79], v[124:125] op_sel_hi:[0,1,1]
	v_pk_fma_f32 v[48:49], v[116:117], v[80:81], v[126:127] op_sel_hi:[0,1,1]
	ds_read_b128 v[50:53], v212 offset:35840
	ds_read_b128 v[62:65], v212 offset:19456
	ds_read_b128 v[54:57], v212 offset:11264
	ds_read_b128 v[58:61], v212 offset:44032
	ds_read_b128 v[66:69], v212 offset:3072
	ds_read2st64_b32 v[110:111], v213 offset0:108 offset1:109
	s_waitcnt lgkmcnt(6)
	v_pk_mul_f32 v[114:115], v[46:47], v[90:91]
	v_pk_mul_f32 v[118:119], v[46:47], v[86:87]
	v_pk_fma_f32 v[114:115], v[48:49], v[92:93], v[114:115]
	v_pk_fma_f32 v[118:119], v[48:49], v[88:89], v[118:119]
	v_add_f32_e32 v116, v114, v115
	v_add_f32_e32 v130, v118, v119
	v_pk_mul_f32 v[120:121], v[102:103], v[112:113] op_sel_hi:[1,0]
	v_add_f32_dpp v116, v116, v116 quad_perm:[1,0,3,2] row_mask:0xf bank_mask:0xf bound_ctrl:1
	v_pk_mul_f32 v[122:123], v[104:105], v[112:113] op_sel_hi:[1,0]
	v_pk_fma_f32 v[124:125], v[46:47], v[94:95], v[120:121]
	v_add_f32_dpp v116, v116, v116 quad_perm:[2,3,0,1] row_mask:0xf bank_mask:0xf bound_ctrl:1
	v_pk_fma_f32 v[126:127], v[48:49], v[96:97], v[122:123]
	v_cndmask_b32_e32 v137, v187, v188, vcc
	v_add_f32_dpp v116, v116, v116 row_ror:4 row_mask:0xf bank_mask:0xf bound_ctrl:1
	v_cndmask_b32_e32 v186, v188, v187, vcc
	s_nop 1
	v_add_f32_dpp v189, v186, v137 quad_perm:[2,3,0,1] row_mask:0xf bank_mask:0xf bound_ctrl:1
	v_add_f32_dpp v116, v116, v116 row_ror:8 row_mask:0xf bank_mask:0xf bound_ctrl:1
	v_pk_fma_f32 v[46:47], v[116:117], v[98:99], v[124:125] op_sel_hi:[0,1,1]
	v_pk_fma_f32 v[48:49], v[116:117], v[100:101], v[126:127] op_sel_hi:[0,1,1]
	ds_read_b128 v[70:73], v212 offset:36096
	ds_read_b128 v[82:85], v212 offset:19712
	ds_read_b128 v[74:77], v212 offset:11520
	ds_read_b128 v[78:81], v212 offset:44288
	ds_read_b128 v[86:89], v212 offset:3328
	v_pk_mul_f32 v[114:115], v[46:47], v[30:31]
	v_pk_mul_f32 v[118:119], v[46:47], v[106:107]
	v_pk_fma_f32 v[114:115], v[48:49], v[32:33], v[114:115]
	v_pk_fma_f32 v[118:119], v[48:49], v[108:109], v[118:119]
	v_add_f32_e32 v116, v114, v115
	v_add_f32_e32 v131, v118, v119
	v_pk_mul_f32 v[120:121], v[42:43], v[112:113] op_sel:[0,1] op_sel_hi:[1,1]
	v_add_f32_dpp v116, v116, v116 quad_perm:[1,0,3,2] row_mask:0xf bank_mask:0xf bound_ctrl:1
	v_pk_mul_f32 v[122:123], v[44:45], v[112:113] op_sel:[0,1] op_sel_hi:[1,1]
	v_pk_fma_f32 v[124:125], v[46:47], v[34:35], v[120:121]
	v_add_f32_dpp v116, v116, v116 quad_perm:[2,3,0,1] row_mask:0xf bank_mask:0xf bound_ctrl:1
	v_pk_fma_f32 v[126:127], v[48:49], v[36:37], v[122:123]
	v_add_f32_dpp v189, v189, v189 row_ror:4 row_mask:0xf bank_mask:0xf bound_ctrl:1
	v_add_f32_dpp v116, v116, v116 row_ror:4 row_mask:0xf bank_mask:0xf bound_ctrl:1
	s_nop 0
	v_add_f32_dpp v189, v189, v189 row_ror:8 row_mask:0xf bank_mask:0xf bound_ctrl:1
	ds_write_b32 v211, v189 offset:256
	v_add_f32_dpp v116, v116, v116 row_ror:8 row_mask:0xf bank_mask:0xf bound_ctrl:1
	v_pk_fma_f32 v[46:47], v[116:117], v[38:39], v[124:125] op_sel_hi:[0,1,1]
	v_pk_fma_f32 v[48:49], v[116:117], v[40:41], v[126:127] op_sel_hi:[0,1,1]
	ds_read_b128 v[90:93], v212 offset:36352
	ds_read_b128 v[102:105], v212 offset:19968
	ds_read_b128 v[94:97], v212 offset:11776
	ds_read_b128 v[98:101], v212 offset:44544
	ds_read_b128 v[106:109], v212 offset:3584
	ds_read2st64_b32 v[112:113], v213 offset0:110 offset1:111
	s_waitcnt lgkmcnt(7)
; __device__ __forceinline__ void rwkv_prompt_unit(const Params& p, int l, int b, int h, int ibase, float* sf) {
;     ...
;             const float* bf_ = sf + (c & 1) * 12288 + jg; float* sY = sYb + (c & 1) * 512; const float* vb_ = sf + (c & 1) * 12288 + 6144 + ibase + rl;
;             f32x4 R[2], W[2], K[2], A[2], B[2]; float V[2];
;     ...
;             RW_LOAD(R, W, K, A, B, V, 0);
;             float pyprev = 0.f;
; #pragma unroll
;             for (int g = 0; g < 16; ++g) {
;                 f32x4 Rn[2], Wn[2], Kn[2], An[2], Bn[2]; float Vn[2];
;                 if (g + 1 < 16) RW_LOAD(Rn, Wn, Kn, An, Bn, Vn, g + 1);
;                 __builtin_amdgcn_sched_barrier(0);
; #pragma unroll
;                 for (int u = 0; u < 2; ++u) {
;                     const f32x2v a01 = {A[u].x, A[u].y}, a23 = {A[u].z, A[u].w}, w01 = {W[u].x, W[u].y}, w23 = {W[u].z, W[u].w}, b01 = {B[u].x, B[u].y}, b23 = {B[u].z, B[u].w};
;                     const f32x2v k01 = {K[u].x, K[u].y}, k23 = {K[u].z, K[u].w}, r01 = {R[u].x, R[u].y}, r23 = {R[u].z, R[u].w};
;                     f32x2v pa = S01 * a01; pa = __builtin_elementwise_fma(S23, a23, pa);
;                     float ra = pa.x + pa.y, rb = pyprev;
;                     ra += dppf<0xB1, 0xF>(ra); rb += dppf<0xB1, 0xF>(rb);
;                     ra += dppf<0x4E, 0xF>(ra); rb += dppf<0x4E, 0xF>(rb);
;                     ra += dppf<0x124, 0xF>(ra); rb += dppf<0x124, 0xF>(rb);
;                     ra += dppf<0x128, 0xF>(ra); rb += dppf<0x128, 0xF>(rb);
;                     if ((g * 2 + u) > 0 && (lane & 15) == 0) sY[(g * 2 + u - 1) * 16 + rl] = rb;
;                     const f32x2v sa2 = {ra, ra}, v2 = {V[u], V[u]};
;                     S01 = __builtin_elementwise_fma(S01, w01, __builtin_elementwise_fma(sa2, b01, v2 * k01));
;                     S23 = __builtin_elementwise_fma(S23, w23, __builtin_elementwise_fma(sa2, b23, v2 * k23));
;                     f32x2v py = S01 * r01; py = __builtin_elementwise_fma(S23, r23, py);
;                     pyprev = py.x + py.y;
;                 }
;                 __builtin_amdgcn_sched_barrier(0);
;                 if (g + 1 < 16) {
; #pragma unroll
;                     for (int u = 0; u < 2; ++u) { R[u] = Rn[u]; W[u] = Wn[u]; K[u] = Kn[u]; A[u] = An[u]; B[u] = Bn[u]; V[u] = Vn[u]; }
;                 }
;             }
	v_pk_mul_f32 v[114:115], v[46:47], v[50:51]
	v_pk_mul_f32 v[118:119], v[46:47], v[140:141]
	v_pk_fma_f32 v[114:115], v[48:49], v[52:53], v[114:115]
	v_pk_fma_f32 v[118:119], v[48:49], v[142:143], v[118:119]
	v_add_f32_e32 v116, v114, v115
	v_add_f32_e32 v132, v118, v119
	v_pk_mul_f32 v[120:121], v[62:63], v[110:111] op_sel_hi:[1,0]
	v_add_f32_dpp v116, v116, v116 quad_perm:[1,0,3,2] row_mask:0xf bank_mask:0xf bound_ctrl:1
	v_pk_mul_f32 v[122:123], v[64:65], v[110:111] op_sel_hi:[1,0]
	v_pk_fma_f32 v[124:125], v[46:47], v[54:55], v[120:121]
	v_add_f32_dpp v116, v116, v116 quad_perm:[2,3,0,1] row_mask:0xf bank_mask:0xf bound_ctrl:1
	v_pk_fma_f32 v[126:127], v[48:49], v[56:57], v[122:123]
	v_cndmask_b32_e64 v137, v129, v130, s[8:9]
	v_add_f32_dpp v116, v116, v116 row_ror:4 row_mask:0xf bank_mask:0xf bound_ctrl:1
	v_cndmask_b32_e64 v186, v130, v129, s[8:9]
	s_nop 1
	v_add_f32_dpp v187, v186, v137 quad_perm:[1,0,3,2] row_mask:0xf bank_mask:0xf bound_ctrl:1
	v_add_f32_dpp v116, v116, v116 row_ror:8 row_mask:0xf bank_mask:0xf bound_ctrl:1
	v_pk_fma_f32 v[46:47], v[116:117], v[58:59], v[124:125] op_sel_hi:[0,1,1]
	v_pk_fma_f32 v[48:49], v[116:117], v[60:61], v[126:127] op_sel_hi:[0,1,1]
	ds_read_b128 v[30:33], v212 offset:36608
	ds_read_b128 v[42:45], v212 offset:20224
	ds_read_b128 v[34:37], v212 offset:12032
	ds_read_b128 v[38:41], v212 offset:44800
	ds_read_b128 v[140:143], v212 offset:3840
	v_pk_mul_f32 v[114:115], v[46:47], v[70:71]
	v_pk_mul_f32 v[118:119], v[46:47], v[66:67]
	v_pk_fma_f32 v[114:115], v[48:49], v[72:73], v[114:115]
	v_pk_fma_f32 v[118:119], v[48:49], v[68:69], v[118:119]
	v_add_f32_e32 v116, v114, v115
	v_add_f32_e32 v133, v118, v119
	v_pk_mul_f32 v[120:121], v[82:83], v[110:111] op_sel:[0,1] op_sel_hi:[1,1]
	v_add_f32_dpp v116, v116, v116 quad_perm:[1,0,3,2] row_mask:0xf bank_mask:0xf bound_ctrl:1
	v_pk_mul_f32 v[122:123], v[84:85], v[110:111] op_sel:[0,1] op_sel_hi:[1,1]
	v_pk_fma_f32 v[124:125], v[46:47], v[74:75], v[120:121]
	v_add_f32_dpp v116, v116, v116 quad_perm:[2,3,0,1] row_mask:0xf bank_mask:0xf bound_ctrl:1
	v_pk_fma_f32 v[126:127], v[48:49], v[76:77], v[122:123]
	v_cndmask_b32_e64 v137, v131, v132, s[8:9]
	v_add_f32_dpp v116, v116, v116 row_ror:4 row_mask:0xf bank_mask:0xf bound_ctrl:1
	v_cndmask_b32_e64 v186, v132, v131, s[8:9]
	s_nop 1
	v_add_f32_dpp v188, v186, v137 quad_perm:[1,0,3,2] row_mask:0xf bank_mask:0xf bound_ctrl:1
	v_add_f32_dpp v116, v116, v116 row_ror:8 row_mask:0xf bank_mask:0xf bound_ctrl:1
	v_pk_fma_f32 v[46:47], v[116:117], v[78:79], v[124:125] op_sel_hi:[0,1,1]
	v_pk_fma_f32 v[48:49], v[116:117], v[80:81], v[126:127] op_sel_hi:[0,1,1]
	ds_read_b128 v[50:53], v212 offset:36864
	ds_read_b128 v[62:65], v212 offset:20480
	ds_read_b128 v[54:57], v212 offset:12288
	ds_read_b128 v[58:61], v212 offset:45056
	ds_read_b128 v[66:69], v212 offset:4096
	ds_read2st64_b32 v[110:111], v213 offset0:112 offset1:113
	s_waitcnt lgkmcnt(6)
	v_pk_mul_f32 v[114:115], v[46:47], v[90:91]
	v_pk_mul_f32 v[118:119], v[46:47], v[86:87]
	v_pk_fma_f32 v[114:115], v[48:49], v[92:93], v[114:115]
	v_pk_fma_f32 v[118:119], v[48:49], v[88:89], v[118:119]
	v_add_f32_e32 v116, v114, v115
	v_add_f32_e32 v134, v118, v119
	v_pk_mul_f32 v[120:121], v[102:103], v[112:113] op_sel_hi:[1,0]
	v_add_f32_dpp v116, v116, v116 quad_perm:[1,0,3,2] row_mask:0xf bank_mask:0xf bound_ctrl:1
	v_pk_mul_f32 v[122:123], v[104:105], v[112:113] op_sel_hi:[1,0]
	v_pk_fma_f32 v[124:125], v[46:47], v[94:95], v[120:121]
	v_add_f32_dpp v116, v116, v116 quad_perm:[2,3,0,1] row_mask:0xf bank_mask:0xf bound_ctrl:1
	v_pk_fma_f32 v[126:127], v[48:49], v[96:97], v[122:123]
	v_cndmask_b32_e32 v137, v187, v188, vcc
	v_add_f32_dpp v116, v116, v116 row_ror:4 row_mask:0xf bank_mask:0xf bound_ctrl:1
	v_cndmask_b32_e32 v186, v188, v187, vcc
	s_nop 1
	v_add_f32_dpp v189, v186, v137 quad_perm:[2,3,0,1] row_mask:0xf bank_mask:0xf bound_ctrl:1
	v_add_f32_dpp v116, v116, v116 row_ror:8 row_mask:0xf bank_mask:0xf bound_ctrl:1
	v_pk_fma_f32 v[46:47], v[116:117], v[98:99], v[124:125] op_sel_hi:[0,1,1]
	v_pk_fma_f32 v[48:49], v[116:117], v[100:101], v[126:127] op_sel_hi:[0,1,1]
	ds_read_b128 v[70:73], v212 offset:37120
	ds_read_b128 v[82:85], v212 offset:20736
	ds_read_b128 v[74:77], v212 offset:12544
	ds_read_b128 v[78:81], v212 offset:45312
	ds_read_b128 v[86:89], v212 offset:4352
	v_pk_mul_f32 v[114:115], v[46:47], v[30:31]
	v_pk_mul_f32 v[118:119], v[46:47], v[106:107]
	v_pk_fma_f32 v[114:115], v[48:49], v[32:33], v[114:115]
	v_pk_fma_f32 v[118:119], v[48:49], v[108:109], v[118:119]
	v_add_f32_e32 v116, v114, v115
	v_add_f32_e32 v135, v118, v119
	v_pk_mul_f32 v[120:121], v[42:43], v[112:113] op_sel:[0,1] op_sel_hi:[1,1]
	v_add_f32_dpp v116, v116, v116 quad_perm:[1,0,3,2] row_mask:0xf bank_mask:0xf bound_ctrl:1
	v_pk_mul_f32 v[122:123], v[44:45], v[112:113] op_sel:[0,1] op_sel_hi:[1,1]
	v_pk_fma_f32 v[124:125], v[46:47], v[34:35], v[120:121]
	v_add_f32_dpp v116, v116, v116 quad_perm:[2,3,0,1] row_mask:0xf bank_mask:0xf bound_ctrl:1
	v_pk_fma_f32 v[126:127], v[48:49], v[36:37], v[122:123]
	v_add_f32_dpp v189, v189, v189 row_ror:4 row_mask:0xf bank_mask:0xf bound_ctrl:1
	v_add_f32_dpp v116, v116, v116 row_ror:4 row_mask:0xf bank_mask:0xf bound_ctrl:1
	s_nop 0
	v_add_f32_dpp v189, v189, v189 row_ror:8 row_mask:0xf bank_mask:0xf bound_ctrl:1
	ds_write_b32 v211, v189 offset:512
	v_add_f32_dpp v116, v116, v116 row_ror:8 row_mask:0xf bank_mask:0xf bound_ctrl:1
	v_pk_fma_f32 v[46:47], v[116:117], v[38:39], v[124:125] op_sel_hi:[0,1,1]
	v_pk_fma_f32 v[48:49], v[116:117], v[40:41], v[126:127] op_sel_hi:[0,1,1]
	ds_read_b128 v[90:93], v212 offset:37376
	ds_read_b128 v[102:105], v212 offset:20992
	ds_read_b128 v[94:97], v212 offset:12800
	ds_read_b128 v[98:101], v212 offset:45568
	ds_read_b128 v[106:109], v212 offset:4608
	ds_read2st64_b32 v[112:113], v213 offset0:114 offset1:115
	s_waitcnt lgkmcnt(7)
; __device__ __forceinline__ void rwkv_prompt_unit(const Params& p, int l, int b, int h, int ibase, float* sf) {
;     ...
;             const float* bf_ = sf + (c & 1) * 12288 + jg; float* sY = sYb + (c & 1) * 512; const float* vb_ = sf + (c & 1) * 12288 + 6144 + ibase + rl;
;             f32x4 R[2], W[2], K[2], A[2], B[2]; float V[2];
;     ...
;             RW_LOAD(R, W, K, A, B, V, 0);
;             float pyprev = 0.f;
; #pragma unroll
;             for (int g = 0; g < 16; ++g) {
;                 f32x4 Rn[2], Wn[2], Kn[2], An[2], Bn[2]; float Vn[2];
;                 if (g + 1 < 16) RW_LOAD(Rn, Wn, Kn, An, Bn, Vn, g + 1);
;                 __builtin_amdgcn_sched_barrier(0);
; #pragma unroll
;                 for (int u = 0; u < 2; ++u) {
;                     const f32x2v a01 = {A[u].x, A[u].y}, a23 = {A[u].z, A[u].w}, w01 = {W[u].x, W[u].y}, w23 = {W[u].z, W[u].w}, b01 = {B[u].x, B[u].y}, b23 = {B[u].z, B[u].w};
;                     const f32x2v k01 = {K[u].x, K[u].y}, k23 = {K[u].z, K[u].w}, r01 = {R[u].x, R[u].y}, r23 = {R[u].z, R[u].w};
;                     f32x2v pa = S01 * a01; pa = __builtin_elementwise_fma(S23, a23, pa);
;                     float ra = pa.x + pa.y, rb = pyprev;
;                     ra += dppf<0xB1, 0xF>(ra); rb += dppf<0xB1, 0xF>(rb);
;                     ra += dppf<0x4E, 0xF>(ra); rb += dppf<0x4E, 0xF>(rb);
;                     ra += dppf<0x124, 0xF>(ra); rb += dppf<0x124, 0xF>(rb);
;                     ra += dppf<0x128, 0xF>(ra); rb += dppf<0x128, 0xF>(rb);
;                     if ((g * 2 + u) > 0 && (lane & 15) == 0) sY[(g * 2 + u - 1) * 16 + rl] = rb;
;                     const f32x2v sa2 = {ra, ra}, v2 = {V[u], V[u]};
;                     S01 = __builtin_elementwise_fma(S01, w01, __builtin_elementwise_fma(sa2, b01, v2 * k01));
;                     S23 = __builtin_elementwise_fma(S23, w23, __builtin_elementwise_fma(sa2, b23, v2 * k23));
;                     f32x2v py = S01 * r01; py = __builtin_elementwise_fma(S23, r23, py);
;                     pyprev = py.x + py.y;
;                 }
;                 __builtin_amdgcn_sched_barrier(0);
;                 if (g + 1 < 16) {
; #pragma unroll
;                     for (int u = 0; u < 2; ++u) { R[u] = Rn[u]; W[u] = Wn[u]; K[u] = Kn[u]; A[u] = An[u]; B[u] = Bn[u]; V[u] = Vn[u]; }
;                 }
;             }
	v_pk_mul_f32 v[114:115], v[46:47], v[50:51]
	v_pk_mul_f32 v[118:119], v[46:47], v[140:141]
	v_pk_fma_f32 v[114:115], v[48:49], v[52:53], v[114:115]
	v_pk_fma_f32 v[118:119], v[48:49], v[142:143], v[118:119]
	v_add_f32_e32 v116, v114, v115
	v_add_f32_e32 v136, v118, v119
	v_pk_mul_f32 v[120:121], v[62:63], v[110:111] op_sel_hi:[1,0]
	v_add_f32_dpp v116, v116, v116 quad_perm:[1,0,3,2] row_mask:0xf bank_mask:0xf bound_ctrl:1
	v_pk_mul_f32 v[122:123], v[64:65], v[110:111] op_sel_hi:[1,0]
	v_pk_fma_f32 v[124:125], v[46:47], v[54:55], v[120:121]
	v_add_f32_dpp v116, v116, v116 quad_perm:[2,3,0,1] row_mask:0xf bank_mask:0xf bound_ctrl:1
	v_pk_fma_f32 v[126:127], v[48:49], v[56:57], v[122:123]
	v_cndmask_b32_e64 v137, v133, v134, s[8:9]
	v_add_f32_dpp v116, v116, v116 row_ror:4 row_mask:0xf bank_mask:0xf bound_ctrl:1
	v_cndmask_b32_e64 v186, v134, v133, s[8:9]
	s_nop 1
	v_add_f32_dpp v187, v186, v137 quad_perm:[1,0,3,2] row_mask:0xf bank_mask:0xf bound_ctrl:1
	v_add_f32_dpp v116, v116, v116 row_ror:8 row_mask:0xf bank_mask:0xf bound_ctrl:1
	v_pk_fma_f32 v[46:47], v[116:117], v[58:59], v[124:125] op_sel_hi:[0,1,1]
	v_pk_fma_f32 v[48:49], v[116:117], v[60:61], v[126:127] op_sel_hi:[0,1,1]
	ds_read_b128 v[30:33], v212 offset:37632
	ds_read_b128 v[42:45], v212 offset:21248
	ds_read_b128 v[34:37], v212 offset:13056
	ds_read_b128 v[38:41], v212 offset:45824
	ds_read_b128 v[140:143], v212 offset:4864
	v_pk_mul_f32 v[114:115], v[46:47], v[70:71]
	v_pk_mul_f32 v[118:119], v[46:47], v[66:67]
	v_pk_fma_f32 v[114:115], v[48:49], v[72:73], v[114:115]
	v_pk_fma_f32 v[118:119], v[48:49], v[68:69], v[118:119]
	v_add_f32_e32 v116, v114, v115
	v_add_f32_e32 v129, v118, v119
	v_pk_mul_f32 v[120:121], v[82:83], v[110:111] op_sel:[0,1] op_sel_hi:[1,1]
	v_add_f32_dpp v116, v116, v116 quad_perm:[1,0,3,2] row_mask:0xf bank_mask:0xf bound_ctrl:1
	v_pk_mul_f32 v[122:123], v[84:85], v[110:111] op_sel:[0,1] op_sel_hi:[1,1]
	v_pk_fma_f32 v[124:125], v[46:47], v[74:75], v[120:121]
	v_add_f32_dpp v116, v116, v116 quad_perm:[2,3,0,1] row_mask:0xf bank_mask:0xf bound_ctrl:1
	v_pk_fma_f32 v[126:127], v[48:49], v[76:77], v[122:123]
	v_cndmask_b32_e64 v137, v135, v136, s[8:9]
	v_add_f32_dpp v116, v116, v116 row_ror:4 row_mask:0xf bank_mask:0xf bound_ctrl:1
	v_cndmask_b32_e64 v186, v136, v135, s[8:9]
	s_nop 1
	v_add_f32_dpp v188, v186, v137 quad_perm:[1,0,3,2] row_mask:0xf bank_mask:0xf bound_ctrl:1
	v_add_f32_dpp v116, v116, v116 row_ror:8 row_mask:0xf bank_mask:0xf bound_ctrl:1
	v_pk_fma_f32 v[46:47], v[116:117], v[78:79], v[124:125] op_sel_hi:[0,1,1]
	v_pk_fma_f32 v[48:49], v[116:117], v[80:81], v[126:127] op_sel_hi:[0,1,1]
	ds_read_b128 v[50:53], v212 offset:37888
	ds_read_b128 v[62:65], v212 offset:21504
	ds_read_b128 v[54:57], v212 offset:13312
	ds_read_b128 v[58:61], v212 offset:46080
	ds_read_b128 v[66:69], v212 offset:5120
	ds_read2st64_b32 v[110:111], v213 offset0:116 offset1:117
	s_waitcnt lgkmcnt(6)
	v_pk_mul_f32 v[114:115], v[46:47], v[90:91]
	v_pk_mul_f32 v[118:119], v[46:47], v[86:87]
	v_pk_fma_f32 v[114:115], v[48:49], v[92:93], v[114:115]
	v_pk_fma_f32 v[118:119], v[48:49], v[88:89], v[118:119]
	v_add_f32_e32 v116, v114, v115
	v_add_f32_e32 v130, v118, v119
	v_pk_mul_f32 v[120:121], v[102:103], v[112:113] op_sel_hi:[1,0]
	v_add_f32_dpp v116, v116, v116 quad_perm:[1,0,3,2] row_mask:0xf bank_mask:0xf bound_ctrl:1
	v_pk_mul_f32 v[122:123], v[104:105], v[112:113] op_sel_hi:[1,0]
	v_pk_fma_f32 v[124:125], v[46:47], v[94:95], v[120:121]
	v_add_f32_dpp v116, v116, v116 quad_perm:[2,3,0,1] row_mask:0xf bank_mask:0xf bound_ctrl:1
	v_pk_fma_f32 v[126:127], v[48:49], v[96:97], v[122:123]
	v_cndmask_b32_e32 v137, v187, v188, vcc
	v_add_f32_dpp v116, v116, v116 row_ror:4 row_mask:0xf bank_mask:0xf bound_ctrl:1
	v_cndmask_b32_e32 v186, v188, v187, vcc
	s_nop 1
	v_add_f32_dpp v189, v186, v137 quad_perm:[2,3,0,1] row_mask:0xf bank_mask:0xf bound_ctrl:1
	v_add_f32_dpp v116, v116, v116 row_ror:8 row_mask:0xf bank_mask:0xf bound_ctrl:1
	v_pk_fma_f32 v[46:47], v[116:117], v[98:99], v[124:125] op_sel_hi:[0,1,1]
	v_pk_fma_f32 v[48:49], v[116:117], v[100:101], v[126:127] op_sel_hi:[0,1,1]
	ds_read_b128 v[70:73], v212 offset:38144
	ds_read_b128 v[82:85], v212 offset:21760
	ds_read_b128 v[74:77], v212 offset:13568
	ds_read_b128 v[78:81], v212 offset:46336
	ds_read_b128 v[86:89], v212 offset:5376
	v_pk_mul_f32 v[114:115], v[46:47], v[30:31]
	v_pk_mul_f32 v[118:119], v[46:47], v[106:107]
	v_pk_fma_f32 v[114:115], v[48:49], v[32:33], v[114:115]
	v_pk_fma_f32 v[118:119], v[48:49], v[108:109], v[118:119]
	v_add_f32_e32 v116, v114, v115
	v_add_f32_e32 v131, v118, v119
	v_pk_mul_f32 v[120:121], v[42:43], v[112:113] op_sel:[0,1] op_sel_hi:[1,1]
	v_add_f32_dpp v116, v116, v116 quad_perm:[1,0,3,2] row_mask:0xf bank_mask:0xf bound_ctrl:1
	v_pk_mul_f32 v[122:123], v[44:45], v[112:113] op_sel:[0,1] op_sel_hi:[1,1]
	v_pk_fma_f32 v[124:125], v[46:47], v[34:35], v[120:121]
	v_add_f32_dpp v116, v116, v116 quad_perm:[2,3,0,1] row_mask:0xf bank_mask:0xf bound_ctrl:1
	v_pk_fma_f32 v[126:127], v[48:49], v[36:37], v[122:123]
	v_add_f32_dpp v189, v189, v189 row_ror:4 row_mask:0xf bank_mask:0xf bound_ctrl:1
	v_add_f32_dpp v116, v116, v116 row_ror:4 row_mask:0xf bank_mask:0xf bound_ctrl:1
	s_nop 0
	v_add_f32_dpp v189, v189, v189 row_ror:8 row_mask:0xf bank_mask:0xf bound_ctrl:1
	ds_write_b32 v211, v189 offset:768
	v_add_f32_dpp v116, v116, v116 row_ror:8 row_mask:0xf bank_mask:0xf bound_ctrl:1
	v_pk_fma_f32 v[46:47], v[116:117], v[38:39], v[124:125] op_sel_hi:[0,1,1]
	v_pk_fma_f32 v[48:49], v[116:117], v[40:41], v[126:127] op_sel_hi:[0,1,1]
	ds_read_b128 v[90:93], v212 offset:38400
	ds_read_b128 v[102:105], v212 offset:22016
	ds_read_b128 v[94:97], v212 offset:13824
	ds_read_b128 v[98:101], v212 offset:46592
	ds_read_b128 v[106:109], v212 offset:5632
	ds_read2st64_b32 v[112:113], v213 offset0:118 offset1:119
	s_waitcnt lgkmcnt(7)
; __device__ __forceinline__ void rwkv_prompt_unit(const Params& p, int l, int b, int h, int ibase, float* sf) {
;     ...
;             const float* bf_ = sf + (c & 1) * 12288 + jg; float* sY = sYb + (c & 1) * 512; const float* vb_ = sf + (c & 1) * 12288 + 6144 + ibase + rl;
;             f32x4 R[2], W[2], K[2], A[2], B[2]; float V[2];
;     ...
;             RW_LOAD(R, W, K, A, B, V, 0);
;             float pyprev = 0.f;
; #pragma unroll
;             for (int g = 0; g < 16; ++g) {
;                 f32x4 Rn[2], Wn[2], Kn[2], An[2], Bn[2]; float Vn[2];
;                 if (g + 1 < 16) RW_LOAD(Rn, Wn, Kn, An, Bn, Vn, g + 1);
;                 __builtin_amdgcn_sched_barrier(0);
; #pragma unroll
;                 for (int u = 0; u < 2; ++u) {
;                     const f32x2v a01 = {A[u].x, A[u].y}, a23 = {A[u].z, A[u].w}, w01 = {W[u].x, W[u].y}, w23 = {W[u].z, W[u].w}, b01 = {B[u].x, B[u].y}, b23 = {B[u].z, B[u].w};
;                     const f32x2v k01 = {K[u].x, K[u].y}, k23 = {K[u].z, K[u].w}, r01 = {R[u].x, R[u].y}, r23 = {R[u].z, R[u].w};
;                     f32x2v pa = S01 * a01; pa = __builtin_elementwise_fma(S23, a23, pa);
;                     float ra = pa.x + pa.y, rb = pyprev;
;                     ra += dppf<0xB1, 0xF>(ra); rb += dppf<0xB1, 0xF>(rb);
;                     ra += dppf<0x4E, 0xF>(ra); rb += dppf<0x4E, 0xF>(rb);
;                     ra += dppf<0x124, 0xF>(ra); rb += dppf<0x124, 0xF>(rb);
;                     ra += dppf<0x128, 0xF>(ra); rb += dppf<0x128, 0xF>(rb);
;                     if ((g * 2 + u) > 0 && (lane & 15) == 0) sY[(g * 2 + u - 1) * 16 + rl] = rb;
;                     const f32x2v sa2 = {ra, ra}, v2 = {V[u], V[u]};
;                     S01 = __builtin_elementwise_fma(S01, w01, __builtin_elementwise_fma(sa2, b01, v2 * k01));
;                     S23 = __builtin_elementwise_fma(S23, w23, __builtin_elementwise_fma(sa2, b23, v2 * k23));
;                     f32x2v py = S01 * r01; py = __builtin_elementwise_fma(S23, r23, py);
;                     pyprev = py.x + py.y;
;                 }
;                 __builtin_amdgcn_sched_barrier(0);
;                 if (g + 1 < 16) {
; #pragma unroll
;                     for (int u = 0; u < 2; ++u) { R[u] = Rn[u]; W[u] = Wn[u]; K[u] = Kn[u]; A[u] = An[u]; B[u] = Bn[u]; V[u] = Vn[u]; }
;                 }
;             }
	v_pk_mul_f32 v[114:115], v[46:47], v[50:51]
	v_pk_mul_f32 v[118:119], v[46:47], v[140:141]
	v_pk_fma_f32 v[114:115], v[48:49], v[52:53], v[114:115]
	v_pk_fma_f32 v[118:119], v[48:49], v[142:143], v[118:119]
	v_add_f32_e32 v116, v114, v115
	v_add_f32_e32 v132, v118, v119
	v_pk_mul_f32 v[120:121], v[62:63], v[110:111] op_sel_hi:[1,0]
	v_add_f32_dpp v116, v116, v116 quad_perm:[1,0,3,2] row_mask:0xf bank_mask:0xf bound_ctrl:1
	v_pk_mul_f32 v[122:123], v[64:65], v[110:111] op_sel_hi:[1,0]
	v_pk_fma_f32 v[124:125], v[46:47], v[54:55], v[120:121]
	v_add_f32_dpp v116, v116, v116 quad_perm:[2,3,0,1] row_mask:0xf bank_mask:0xf bound_ctrl:1
	v_pk_fma_f32 v[126:127], v[48:49], v[56:57], v[122:123]
	v_cndmask_b32_e64 v137, v129, v130, s[8:9]
	v_add_f32_dpp v116, v116, v116 row_ror:4 row_mask:0xf bank_mask:0xf bound_ctrl:1
	v_cndmask_b32_e64 v186, v130, v129, s[8:9]
	s_nop 1
	v_add_f32_dpp v187, v186, v137 quad_perm:[1,0,3,2] row_mask:0xf bank_mask:0xf bound_ctrl:1
	v_add_f32_dpp v116, v116, v116 row_ror:8 row_mask:0xf bank_mask:0xf bound_ctrl:1
	v_pk_fma_f32 v[46:47], v[116:117], v[58:59], v[124:125] op_sel_hi:[0,1,1]
	v_pk_fma_f32 v[48:49], v[116:117], v[60:61], v[126:127] op_sel_hi:[0,1,1]
	ds_read_b128 v[30:33], v212 offset:38656
	ds_read_b128 v[42:45], v212 offset:22272
	ds_read_b128 v[34:37], v212 offset:14080
	ds_read_b128 v[38:41], v212 offset:46848
	ds_read_b128 v[140:143], v212 offset:5888
	v_pk_mul_f32 v[114:115], v[46:47], v[70:71]
	v_pk_mul_f32 v[118:119], v[46:47], v[66:67]
	v_pk_fma_f32 v[114:115], v[48:49], v[72:73], v[114:115]
	v_pk_fma_f32 v[118:119], v[48:49], v[68:69], v[118:119]
	v_add_f32_e32 v116, v114, v115
	v_add_f32_e32 v133, v118, v119
	v_pk_mul_f32 v[120:121], v[82:83], v[110:111] op_sel:[0,1] op_sel_hi:[1,1]
	v_add_f32_dpp v116, v116, v116 quad_perm:[1,0,3,2] row_mask:0xf bank_mask:0xf bound_ctrl:1
	v_pk_mul_f32 v[122:123], v[84:85], v[110:111] op_sel:[0,1] op_sel_hi:[1,1]
	v_pk_fma_f32 v[124:125], v[46:47], v[74:75], v[120:121]
	v_add_f32_dpp v116, v116, v116 quad_perm:[2,3,0,1] row_mask:0xf bank_mask:0xf bound_ctrl:1
	v_pk_fma_f32 v[126:127], v[48:49], v[76:77], v[122:123]
	v_cndmask_b32_e64 v137, v131, v132, s[8:9]
	v_add_f32_dpp v116, v116, v116 row_ror:4 row_mask:0xf bank_mask:0xf bound_ctrl:1
	v_cndmask_b32_e64 v186, v132, v131, s[8:9]
	s_nop 1
	v_add_f32_dpp v188, v186, v137 quad_perm:[1,0,3,2] row_mask:0xf bank_mask:0xf bound_ctrl:1
	v_add_f32_dpp v116, v116, v116 row_ror:8 row_mask:0xf bank_mask:0xf bound_ctrl:1
	v_pk_fma_f32 v[46:47], v[116:117], v[78:79], v[124:125] op_sel_hi:[0,1,1]
	v_pk_fma_f32 v[48:49], v[116:117], v[80:81], v[126:127] op_sel_hi:[0,1,1]
	ds_read_b128 v[50:53], v212 offset:38912
	ds_read_b128 v[62:65], v212 offset:22528
	ds_read_b128 v[54:57], v212 offset:14336
	ds_read_b128 v[58:61], v212 offset:47104
	ds_read_b128 v[66:69], v212 offset:6144
	ds_read2st64_b32 v[110:111], v213 offset0:120 offset1:121
	s_waitcnt lgkmcnt(6)
	v_pk_mul_f32 v[114:115], v[46:47], v[90:91]
	v_pk_mul_f32 v[118:119], v[46:47], v[86:87]
	v_pk_fma_f32 v[114:115], v[48:49], v[92:93], v[114:115]
	v_pk_fma_f32 v[118:119], v[48:49], v[88:89], v[118:119]
	v_add_f32_e32 v116, v114, v115
	v_add_f32_e32 v134, v118, v119
	v_pk_mul_f32 v[120:121], v[102:103], v[112:113] op_sel_hi:[1,0]
	v_add_f32_dpp v116, v116, v116 quad_perm:[1,0,3,2] row_mask:0xf bank_mask:0xf bound_ctrl:1
	v_pk_mul_f32 v[122:123], v[104:105], v[112:113] op_sel_hi:[1,0]
	v_pk_fma_f32 v[124:125], v[46:47], v[94:95], v[120:121]
	v_add_f32_dpp v116, v116, v116 quad_perm:[2,3,0,1] row_mask:0xf bank_mask:0xf bound_ctrl:1
	v_pk_fma_f32 v[126:127], v[48:49], v[96:97], v[122:123]
	v_cndmask_b32_e32 v137, v187, v188, vcc
	v_add_f32_dpp v116, v116, v116 row_ror:4 row_mask:0xf bank_mask:0xf bound_ctrl:1
	v_cndmask_b32_e32 v186, v188, v187, vcc
	s_nop 1
	v_add_f32_dpp v189, v186, v137 quad_perm:[2,3,0,1] row_mask:0xf bank_mask:0xf bound_ctrl:1
	v_add_f32_dpp v116, v116, v116 row_ror:8 row_mask:0xf bank_mask:0xf bound_ctrl:1
	v_pk_fma_f32 v[46:47], v[116:117], v[98:99], v[124:125] op_sel_hi:[0,1,1]
	v_pk_fma_f32 v[48:49], v[116:117], v[100:101], v[126:127] op_sel_hi:[0,1,1]
	ds_read_b128 v[70:73], v212 offset:39168
	ds_read_b128 v[82:85], v212 offset:22784
	ds_read_b128 v[74:77], v212 offset:14592
	ds_read_b128 v[78:81], v212 offset:47360
	ds_read_b128 v[86:89], v212 offset:6400
	v_pk_mul_f32 v[114:115], v[46:47], v[30:31]
	v_pk_mul_f32 v[118:119], v[46:47], v[106:107]
	v_pk_fma_f32 v[114:115], v[48:49], v[32:33], v[114:115]
	v_pk_fma_f32 v[118:119], v[48:49], v[108:109], v[118:119]
	v_add_f32_e32 v116, v114, v115
	v_add_f32_e32 v135, v118, v119
	v_pk_mul_f32 v[120:121], v[42:43], v[112:113] op_sel:[0,1] op_sel_hi:[1,1]
	v_add_f32_dpp v116, v116, v116 quad_perm:[1,0,3,2] row_mask:0xf bank_mask:0xf bound_ctrl:1
	v_pk_mul_f32 v[122:123], v[44:45], v[112:113] op_sel:[0,1] op_sel_hi:[1,1]
	v_pk_fma_f32 v[124:125], v[46:47], v[34:35], v[120:121]
	v_add_f32_dpp v116, v116, v116 quad_perm:[2,3,0,1] row_mask:0xf bank_mask:0xf bound_ctrl:1
	v_pk_fma_f32 v[126:127], v[48:49], v[36:37], v[122:123]
	v_add_f32_dpp v189, v189, v189 row_ror:4 row_mask:0xf bank_mask:0xf bound_ctrl:1
	v_add_f32_dpp v116, v116, v116 row_ror:4 row_mask:0xf bank_mask:0xf bound_ctrl:1
	s_nop 0
	v_add_f32_dpp v189, v189, v189 row_ror:8 row_mask:0xf bank_mask:0xf bound_ctrl:1
	ds_write_b32 v211, v189 offset:1024
	v_add_f32_dpp v116, v116, v116 row_ror:8 row_mask:0xf bank_mask:0xf bound_ctrl:1
	v_pk_fma_f32 v[46:47], v[116:117], v[38:39], v[124:125] op_sel_hi:[0,1,1]
	v_pk_fma_f32 v[48:49], v[116:117], v[40:41], v[126:127] op_sel_hi:[0,1,1]
	ds_read_b128 v[90:93], v212 offset:39424
	ds_read_b128 v[102:105], v212 offset:23040
	ds_read_b128 v[94:97], v212 offset:14848
	ds_read_b128 v[98:101], v212 offset:47616
	ds_read_b128 v[106:109], v212 offset:6656
	ds_read2st64_b32 v[112:113], v213 offset0:122 offset1:123
	s_waitcnt lgkmcnt(7)
; __device__ __forceinline__ void rwkv_prompt_unit(const Params& p, int l, int b, int h, int ibase, float* sf) {
;     ...
;             const float* bf_ = sf + (c & 1) * 12288 + jg; float* sY = sYb + (c & 1) * 512; const float* vb_ = sf + (c & 1) * 12288 + 6144 + ibase + rl;
;             f32x4 R[2], W[2], K[2], A[2], B[2]; float V[2];
;     ...
;             RW_LOAD(R, W, K, A, B, V, 0);
;             float pyprev = 0.f;
; #pragma unroll
;             for (int g = 0; g < 16; ++g) {
;                 f32x4 Rn[2], Wn[2], Kn[2], An[2], Bn[2]; float Vn[2];
;                 if (g + 1 < 16) RW_LOAD(Rn, Wn, Kn, An, Bn, Vn, g + 1);
;                 __builtin_amdgcn_sched_barrier(0);
; #pragma unroll
;                 for (int u = 0; u < 2; ++u) {
;                     const f32x2v a01 = {A[u].x, A[u].y}, a23 = {A[u].z, A[u].w}, w01 = {W[u].x, W[u].y}, w23 = {W[u].z, W[u].w}, b01 = {B[u].x, B[u].y}, b23 = {B[u].z, B[u].w};
;                     const f32x2v k01 = {K[u].x, K[u].y}, k23 = {K[u].z, K[u].w}, r01 = {R[u].x, R[u].y}, r23 = {R[u].z, R[u].w};
;                     f32x2v pa = S01 * a01; pa = __builtin_elementwise_fma(S23, a23, pa);
;                     float ra = pa.x + pa.y, rb = pyprev;
;                     ra += dppf<0xB1, 0xF>(ra); rb += dppf<0xB1, 0xF>(rb);
;                     ra += dppf<0x4E, 0xF>(ra); rb += dppf<0x4E, 0xF>(rb);
;                     ra += dppf<0x124, 0xF>(ra); rb += dppf<0x124, 0xF>(rb);
;                     ra += dppf<0x128, 0xF>(ra); rb += dppf<0x128, 0xF>(rb);
;                     if ((g * 2 + u) > 0 && (lane & 15) == 0) sY[(g * 2 + u - 1) * 16 + rl] = rb;
;                     const f32x2v sa2 = {ra, ra}, v2 = {V[u], V[u]};
;                     S01 = __builtin_elementwise_fma(S01, w01, __builtin_elementwise_fma(sa2, b01, v2 * k01));
;                     S23 = __builtin_elementwise_fma(S23, w23, __builtin_elementwise_fma(sa2, b23, v2 * k23));
;                     f32x2v py = S01 * r01; py = __builtin_elementwise_fma(S23, r23, py);
;                     pyprev = py.x + py.y;
;                 }
;                 __builtin_amdgcn_sched_barrier(0);
;                 if (g + 1 < 16) {
; #pragma unroll
;                     for (int u = 0; u < 2; ++u) { R[u] = Rn[u]; W[u] = Wn[u]; K[u] = Kn[u]; A[u] = An[u]; B[u] = Bn[u]; V[u] = Vn[u]; }
;                 }
;             }
	v_pk_mul_f32 v[114:115], v[46:47], v[50:51]
	v_pk_mul_f32 v[118:119], v[46:47], v[140:141]
	v_pk_fma_f32 v[114:115], v[48:49], v[52:53], v[114:115]
	v_pk_fma_f32 v[118:119], v[48:49], v[142:143], v[118:119]
	v_add_f32_e32 v116, v114, v115
	v_add_f32_e32 v136, v118, v119
	v_pk_mul_f32 v[120:121], v[62:63], v[110:111] op_sel_hi:[1,0]
	v_add_f32_dpp v116, v116, v116 quad_perm:[1,0,3,2] row_mask:0xf bank_mask:0xf bound_ctrl:1
	v_pk_mul_f32 v[122:123], v[64:65], v[110:111] op_sel_hi:[1,0]
	v_pk_fma_f32 v[124:125], v[46:47], v[54:55], v[120:121]
	v_add_f32_dpp v116, v116, v116 quad_perm:[2,3,0,1] row_mask:0xf bank_mask:0xf bound_ctrl:1
	v_pk_fma_f32 v[126:127], v[48:49], v[56:57], v[122:123]
	v_cndmask_b32_e64 v137, v133, v134, s[8:9]
	v_add_f32_dpp v116, v116, v116 row_ror:4 row_mask:0xf bank_mask:0xf bound_ctrl:1
	v_cndmask_b32_e64 v186, v134, v133, s[8:9]
	s_nop 1
	v_add_f32_dpp v187, v186, v137 quad_perm:[1,0,3,2] row_mask:0xf bank_mask:0xf bound_ctrl:1
	v_add_f32_dpp v116, v116, v116 row_ror:8 row_mask:0xf bank_mask:0xf bound_ctrl:1
	v_pk_fma_f32 v[46:47], v[116:117], v[58:59], v[124:125] op_sel_hi:[0,1,1]
	v_pk_fma_f32 v[48:49], v[116:117], v[60:61], v[126:127] op_sel_hi:[0,1,1]
	ds_read_b128 v[30:33], v212 offset:39680
	ds_read_b128 v[42:45], v212 offset:23296
	ds_read_b128 v[34:37], v212 offset:15104
	ds_read_b128 v[38:41], v212 offset:47872
	ds_read_b128 v[140:143], v212 offset:6912
	v_pk_mul_f32 v[114:115], v[46:47], v[70:71]
	v_pk_mul_f32 v[118:119], v[46:47], v[66:67]
	v_pk_fma_f32 v[114:115], v[48:49], v[72:73], v[114:115]
	v_pk_fma_f32 v[118:119], v[48:49], v[68:69], v[118:119]
	v_add_f32_e32 v116, v114, v115
	v_add_f32_e32 v129, v118, v119
	v_pk_mul_f32 v[120:121], v[82:83], v[110:111] op_sel:[0,1] op_sel_hi:[1,1]
	v_add_f32_dpp v116, v116, v116 quad_perm:[1,0,3,2] row_mask:0xf bank_mask:0xf bound_ctrl:1
	v_pk_mul_f32 v[122:123], v[84:85], v[110:111] op_sel:[0,1] op_sel_hi:[1,1]
	v_pk_fma_f32 v[124:125], v[46:47], v[74:75], v[120:121]
	v_add_f32_dpp v116, v116, v116 quad_perm:[2,3,0,1] row_mask:0xf bank_mask:0xf bound_ctrl:1
	v_pk_fma_f32 v[126:127], v[48:49], v[76:77], v[122:123]
	v_cndmask_b32_e64 v137, v135, v136, s[8:9]
	v_add_f32_dpp v116, v116, v116 row_ror:4 row_mask:0xf bank_mask:0xf bound_ctrl:1
	v_cndmask_b32_e64 v186, v136, v135, s[8:9]
	s_nop 1
	v_add_f32_dpp v188, v186, v137 quad_perm:[1,0,3,2] row_mask:0xf bank_mask:0xf bound_ctrl:1
	v_add_f32_dpp v116, v116, v116 row_ror:8 row_mask:0xf bank_mask:0xf bound_ctrl:1
	v_pk_fma_f32 v[46:47], v[116:117], v[78:79], v[124:125] op_sel_hi:[0,1,1]
	v_pk_fma_f32 v[48:49], v[116:117], v[80:81], v[126:127] op_sel_hi:[0,1,1]
	ds_read_b128 v[50:53], v212 offset:39936
	ds_read_b128 v[62:65], v212 offset:23552
	ds_read_b128 v[54:57], v212 offset:15360
	ds_read_b128 v[58:61], v212 offset:48128
	ds_read_b128 v[66:69], v212 offset:7168
	ds_read2st64_b32 v[110:111], v213 offset0:124 offset1:125
	s_waitcnt lgkmcnt(6)
	v_pk_mul_f32 v[114:115], v[46:47], v[90:91]
	v_pk_mul_f32 v[118:119], v[46:47], v[86:87]
	v_pk_fma_f32 v[114:115], v[48:49], v[92:93], v[114:115]
	v_pk_fma_f32 v[118:119], v[48:49], v[88:89], v[118:119]
	v_add_f32_e32 v116, v114, v115
	v_add_f32_e32 v130, v118, v119
	v_pk_mul_f32 v[120:121], v[102:103], v[112:113] op_sel_hi:[1,0]
	v_add_f32_dpp v116, v116, v116 quad_perm:[1,0,3,2] row_mask:0xf bank_mask:0xf bound_ctrl:1
	v_pk_mul_f32 v[122:123], v[104:105], v[112:113] op_sel_hi:[1,0]
	v_pk_fma_f32 v[124:125], v[46:47], v[94:95], v[120:121]
	v_add_f32_dpp v116, v116, v116 quad_perm:[2,3,0,1] row_mask:0xf bank_mask:0xf bound_ctrl:1
	v_pk_fma_f32 v[126:127], v[48:49], v[96:97], v[122:123]
	v_cndmask_b32_e32 v137, v187, v188, vcc
	v_add_f32_dpp v116, v116, v116 row_ror:4 row_mask:0xf bank_mask:0xf bound_ctrl:1
	v_cndmask_b32_e32 v186, v188, v187, vcc
	s_nop 1
	v_add_f32_dpp v189, v186, v137 quad_perm:[2,3,0,1] row_mask:0xf bank_mask:0xf bound_ctrl:1
	v_add_f32_dpp v116, v116, v116 row_ror:8 row_mask:0xf bank_mask:0xf bound_ctrl:1
	v_pk_fma_f32 v[46:47], v[116:117], v[98:99], v[124:125] op_sel_hi:[0,1,1]
	v_pk_fma_f32 v[48:49], v[116:117], v[100:101], v[126:127] op_sel_hi:[0,1,1]
	ds_read_b128 v[70:73], v212 offset:40192
	ds_read_b128 v[82:85], v212 offset:23808
	ds_read_b128 v[74:77], v212 offset:15616
	ds_read_b128 v[78:81], v212 offset:48384
	ds_read_b128 v[86:89], v212 offset:7424
	v_pk_mul_f32 v[114:115], v[46:47], v[30:31]
	v_pk_mul_f32 v[118:119], v[46:47], v[106:107]
	v_pk_fma_f32 v[114:115], v[48:49], v[32:33], v[114:115]
	v_pk_fma_f32 v[118:119], v[48:49], v[108:109], v[118:119]
	v_add_f32_e32 v116, v114, v115
	v_add_f32_e32 v131, v118, v119
	v_pk_mul_f32 v[120:121], v[42:43], v[112:113] op_sel:[0,1] op_sel_hi:[1,1]
	v_add_f32_dpp v116, v116, v116 quad_perm:[1,0,3,2] row_mask:0xf bank_mask:0xf bound_ctrl:1
	v_pk_mul_f32 v[122:123], v[44:45], v[112:113] op_sel:[0,1] op_sel_hi:[1,1]
	v_pk_fma_f32 v[124:125], v[46:47], v[34:35], v[120:121]
	v_add_f32_dpp v116, v116, v116 quad_perm:[2,3,0,1] row_mask:0xf bank_mask:0xf bound_ctrl:1
	v_pk_fma_f32 v[126:127], v[48:49], v[36:37], v[122:123]
	v_add_f32_dpp v189, v189, v189 row_ror:4 row_mask:0xf bank_mask:0xf bound_ctrl:1
	v_add_f32_dpp v116, v116, v116 row_ror:4 row_mask:0xf bank_mask:0xf bound_ctrl:1
	s_nop 0
	v_add_f32_dpp v189, v189, v189 row_ror:8 row_mask:0xf bank_mask:0xf bound_ctrl:1
	ds_write_b32 v211, v189 offset:1280
	v_add_f32_dpp v116, v116, v116 row_ror:8 row_mask:0xf bank_mask:0xf bound_ctrl:1
	v_pk_fma_f32 v[46:47], v[116:117], v[38:39], v[124:125] op_sel_hi:[0,1,1]
	v_pk_fma_f32 v[48:49], v[116:117], v[40:41], v[126:127] op_sel_hi:[0,1,1]
	ds_read_b128 v[90:93], v212 offset:40448
	ds_read_b128 v[102:105], v212 offset:24064
	ds_read_b128 v[94:97], v212 offset:15872
	ds_read_b128 v[98:101], v212 offset:48640
	ds_read_b128 v[106:109], v212 offset:7680
	ds_read2st64_b32 v[112:113], v213 offset0:126 offset1:127
	s_waitcnt lgkmcnt(7)
; __device__ __forceinline__ void rwkv_prompt_unit(const Params& p, int l, int b, int h, int ibase, float* sf) {
;     ...
;             const float* bf_ = sf + (c & 1) * 12288 + jg; float* sY = sYb + (c & 1) * 512; const float* vb_ = sf + (c & 1) * 12288 + 6144 + ibase + rl;
;             f32x4 R[2], W[2], K[2], A[2], B[2]; float V[2];
;     ...
;             RW_LOAD(R, W, K, A, B, V, 0);
;             float pyprev = 0.f;
; #pragma unroll
;             for (int g = 0; g < 16; ++g) {
;                 f32x4 Rn[2], Wn[2], Kn[2], An[2], Bn[2]; float Vn[2];
;                 if (g + 1 < 16) RW_LOAD(Rn, Wn, Kn, An, Bn, Vn, g + 1);
;                 __builtin_amdgcn_sched_barrier(0);
; #pragma unroll
;                 for (int u = 0; u < 2; ++u) {
;                     const f32x2v a01 = {A[u].x, A[u].y}, a23 = {A[u].z, A[u].w}, w01 = {W[u].x, W[u].y}, w23 = {W[u].z, W[u].w}, b01 = {B[u].x, B[u].y}, b23 = {B[u].z, B[u].w};
;                     const f32x2v k01 = {K[u].x, K[u].y}, k23 = {K[u].z, K[u].w}, r01 = {R[u].x, R[u].y}, r23 = {R[u].z, R[u].w};
;                     f32x2v pa = S01 * a01; pa = __builtin_elementwise_fma(S23, a23, pa);
;                     float ra = pa.x + pa.y, rb = pyprev;
;                     ra += dppf<0xB1, 0xF>(ra); rb += dppf<0xB1, 0xF>(rb);
;                     ra += dppf<0x4E, 0xF>(ra); rb += dppf<0x4E, 0xF>(rb);
;                     ra += dppf<0x124, 0xF>(ra); rb += dppf<0x124, 0xF>(rb);
;                     ra += dppf<0x128, 0xF>(ra); rb += dppf<0x128, 0xF>(rb);
;                     if ((g * 2 + u) > 0 && (lane & 15) == 0) sY[(g * 2 + u - 1) * 16 + rl] = rb;
;                     const f32x2v sa2 = {ra, ra}, v2 = {V[u], V[u]};
;                     S01 = __builtin_elementwise_fma(S01, w01, __builtin_elementwise_fma(sa2, b01, v2 * k01));
;                     S23 = __builtin_elementwise_fma(S23, w23, __builtin_elementwise_fma(sa2, b23, v2 * k23));
;                     f32x2v py = S01 * r01; py = __builtin_elementwise_fma(S23, r23, py);
;                     pyprev = py.x + py.y;
;                 }
;                 __builtin_amdgcn_sched_barrier(0);
;                 if (g + 1 < 16) {
; #pragma unroll
;                     for (int u = 0; u < 2; ++u) { R[u] = Rn[u]; W[u] = Wn[u]; K[u] = Kn[u]; A[u] = An[u]; B[u] = Bn[u]; V[u] = Vn[u]; }
;                 }
;             }
	v_pk_mul_f32 v[114:115], v[46:47], v[50:51]
	v_pk_mul_f32 v[118:119], v[46:47], v[140:141]
	v_pk_fma_f32 v[114:115], v[48:49], v[52:53], v[114:115]
	v_pk_fma_f32 v[118:119], v[48:49], v[142:143], v[118:119]
	v_add_f32_e32 v116, v114, v115
	v_add_f32_e32 v132, v118, v119
	v_pk_mul_f32 v[120:121], v[62:63], v[110:111] op_sel_hi:[1,0]
	v_add_f32_dpp v116, v116, v116 quad_perm:[1,0,3,2] row_mask:0xf bank_mask:0xf bound_ctrl:1
	v_pk_mul_f32 v[122:123], v[64:65], v[110:111] op_sel_hi:[1,0]
	v_pk_fma_f32 v[124:125], v[46:47], v[54:55], v[120:121]
	v_add_f32_dpp v116, v116, v116 quad_perm:[2,3,0,1] row_mask:0xf bank_mask:0xf bound_ctrl:1
	v_pk_fma_f32 v[126:127], v[48:49], v[56:57], v[122:123]
	v_cndmask_b32_e64 v137, v129, v130, s[8:9]
	v_add_f32_dpp v116, v116, v116 row_ror:4 row_mask:0xf bank_mask:0xf bound_ctrl:1
	v_cndmask_b32_e64 v186, v130, v129, s[8:9]
	s_nop 1
	v_add_f32_dpp v187, v186, v137 quad_perm:[1,0,3,2] row_mask:0xf bank_mask:0xf bound_ctrl:1
	v_add_f32_dpp v116, v116, v116 row_ror:8 row_mask:0xf bank_mask:0xf bound_ctrl:1
	v_pk_fma_f32 v[46:47], v[116:117], v[58:59], v[124:125] op_sel_hi:[0,1,1]
	v_pk_fma_f32 v[48:49], v[116:117], v[60:61], v[126:127] op_sel_hi:[0,1,1]
	ds_read_b128 v[30:33], v212 offset:40704
	ds_read_b128 v[42:45], v212 offset:24320
	ds_read_b128 v[34:37], v212 offset:16128
	ds_read_b128 v[38:41], v212 offset:48896
	ds_read_b128 v[140:143], v212 offset:7936
	v_pk_mul_f32 v[114:115], v[46:47], v[70:71]
	v_pk_mul_f32 v[118:119], v[46:47], v[66:67]
	v_pk_fma_f32 v[114:115], v[48:49], v[72:73], v[114:115]
	v_pk_fma_f32 v[118:119], v[48:49], v[68:69], v[118:119]
	v_add_f32_e32 v116, v114, v115
	v_add_f32_e32 v133, v118, v119
	v_pk_mul_f32 v[120:121], v[82:83], v[110:111] op_sel:[0,1] op_sel_hi:[1,1]
	v_add_f32_dpp v116, v116, v116 quad_perm:[1,0,3,2] row_mask:0xf bank_mask:0xf bound_ctrl:1
	v_pk_mul_f32 v[122:123], v[84:85], v[110:111] op_sel:[0,1] op_sel_hi:[1,1]
	v_pk_fma_f32 v[124:125], v[46:47], v[74:75], v[120:121]
	v_add_f32_dpp v116, v116, v116 quad_perm:[2,3,0,1] row_mask:0xf bank_mask:0xf bound_ctrl:1
	v_pk_fma_f32 v[126:127], v[48:49], v[76:77], v[122:123]
	v_cndmask_b32_e64 v137, v131, v132, s[8:9]
	v_add_f32_dpp v116, v116, v116 row_ror:4 row_mask:0xf bank_mask:0xf bound_ctrl:1
	v_cndmask_b32_e64 v186, v132, v131, s[8:9]
	s_nop 1
	v_add_f32_dpp v188, v186, v137 quad_perm:[1,0,3,2] row_mask:0xf bank_mask:0xf bound_ctrl:1
	v_add_f32_dpp v116, v116, v116 row_ror:8 row_mask:0xf bank_mask:0xf bound_ctrl:1
	v_pk_fma_f32 v[46:47], v[116:117], v[78:79], v[124:125] op_sel_hi:[0,1,1]
	v_pk_fma_f32 v[48:49], v[116:117], v[80:81], v[126:127] op_sel_hi:[0,1,1]
	s_waitcnt lgkmcnt(0)
	v_pk_mul_f32 v[114:115], v[46:47], v[90:91]
	v_pk_mul_f32 v[118:119], v[46:47], v[86:87]
	v_pk_fma_f32 v[114:115], v[48:49], v[92:93], v[114:115]
	v_pk_fma_f32 v[118:119], v[48:49], v[88:89], v[118:119]
	v_add_f32_e32 v116, v114, v115
	v_add_f32_e32 v134, v118, v119
	v_pk_mul_f32 v[120:121], v[102:103], v[112:113] op_sel_hi:[1,0]
	v_add_f32_dpp v116, v116, v116 quad_perm:[1,0,3,2] row_mask:0xf bank_mask:0xf bound_ctrl:1
	v_pk_mul_f32 v[122:123], v[104:105], v[112:113] op_sel_hi:[1,0]
	v_pk_fma_f32 v[124:125], v[46:47], v[94:95], v[120:121]
	v_add_f32_dpp v116, v116, v116 quad_perm:[2,3,0,1] row_mask:0xf bank_mask:0xf bound_ctrl:1
	v_pk_fma_f32 v[126:127], v[48:49], v[96:97], v[122:123]
	v_cndmask_b32_e32 v137, v187, v188, vcc
	v_add_f32_dpp v116, v116, v116 row_ror:4 row_mask:0xf bank_mask:0xf bound_ctrl:1
	v_cndmask_b32_e32 v186, v188, v187, vcc
	s_nop 1
	v_add_f32_dpp v189, v186, v137 quad_perm:[2,3,0,1] row_mask:0xf bank_mask:0xf bound_ctrl:1
	v_add_f32_dpp v116, v116, v116 row_ror:8 row_mask:0xf bank_mask:0xf bound_ctrl:1
	v_pk_fma_f32 v[46:47], v[116:117], v[98:99], v[124:125] op_sel_hi:[0,1,1]
	v_pk_fma_f32 v[48:49], v[116:117], v[100:101], v[126:127] op_sel_hi:[0,1,1]
	v_pk_mul_f32 v[114:115], v[46:47], v[30:31]
	v_pk_mul_f32 v[118:119], v[46:47], v[106:107]
	v_pk_fma_f32 v[114:115], v[48:49], v[32:33], v[114:115]
	v_pk_fma_f32 v[118:119], v[48:49], v[108:109], v[118:119]
	v_add_f32_e32 v116, v114, v115
	v_add_f32_e32 v135, v118, v119
	v_pk_mul_f32 v[120:121], v[42:43], v[112:113] op_sel:[0,1] op_sel_hi:[1,1]
	v_add_f32_dpp v116, v116, v116 quad_perm:[1,0,3,2] row_mask:0xf bank_mask:0xf bound_ctrl:1
	v_pk_mul_f32 v[122:123], v[44:45], v[112:113] op_sel:[0,1] op_sel_hi:[1,1]
	v_pk_fma_f32 v[124:125], v[46:47], v[34:35], v[120:121]
	v_add_f32_dpp v116, v116, v116 quad_perm:[2,3,0,1] row_mask:0xf bank_mask:0xf bound_ctrl:1
	v_pk_fma_f32 v[126:127], v[48:49], v[36:37], v[122:123]
	v_add_f32_dpp v189, v189, v189 row_ror:4 row_mask:0xf bank_mask:0xf bound_ctrl:1
	v_add_f32_dpp v116, v116, v116 row_ror:4 row_mask:0xf bank_mask:0xf bound_ctrl:1
	s_nop 0
	v_add_f32_dpp v189, v189, v189 row_ror:8 row_mask:0xf bank_mask:0xf bound_ctrl:1
	ds_write_b32 v211, v189 offset:1536
	v_add_f32_dpp v116, v116, v116 row_ror:8 row_mask:0xf bank_mask:0xf bound_ctrl:1
	v_pk_fma_f32 v[46:47], v[116:117], v[38:39], v[124:125] op_sel_hi:[0,1,1]
	v_pk_fma_f32 v[48:49], v[116:117], v[40:41], v[126:127] op_sel_hi:[0,1,1]
	v_pk_mul_f32 v[118:119], v[46:47], v[140:141]
	s_nop 0
	v_pk_fma_f32 v[118:119], v[48:49], v[142:143], v[118:119]
	s_nop 0
	v_add_f32_e32 v136, v118, v119
	v_cndmask_b32_e64 v137, v133, v134, s[8:9]
	v_cndmask_b32_e64 v186, v134, v133, s[8:9]
	s_nop 1
	v_add_f32_dpp v187, v186, v137 quad_perm:[1,0,3,2] row_mask:0xf bank_mask:0xf bound_ctrl:1
	v_cndmask_b32_e64 v137, v135, v136, s[8:9]
	v_cndmask_b32_e64 v186, v136, v135, s[8:9]
	s_nop 1
	v_add_f32_dpp v188, v186, v137 quad_perm:[1,0,3,2] row_mask:0xf bank_mask:0xf bound_ctrl:1
	v_cndmask_b32_e32 v137, v187, v188, vcc
	v_cndmask_b32_e32 v186, v188, v187, vcc
	s_nop 1
	v_add_f32_dpp v189, v186, v137 quad_perm:[2,3,0,1] row_mask:0xf bank_mask:0xf bound_ctrl:1
	s_nop 1
	v_add_f32_dpp v189, v189, v189 row_ror:4 row_mask:0xf bank_mask:0xf bound_ctrl:1
	s_nop 1
	v_add_f32_dpp v189, v189, v189 row_ror:8 row_mask:0xf bank_mask:0xf bound_ctrl:1
	ds_write_b32 v211, v189 offset:1792
	s_setprio 0
	s_branch .LBB0_955
